# batched the stick-breaking item output epilogue (16 serialized load-wait-store round trips per thread become 16 loads, one wait, 16 stores) on top of the XCD barrier and the K/V projection tiles in th
# speedup vs baseline: 1.0107x; 1.0107x over previous
; #define RUN(PH, BIT, CALL) if (ph_lo <= (PH) && (PH) <= ph_hi) { if (ONLY & (BIT)) { CALL; } if ((PH) < ph_hi && coop) cg::this_grid().sync(); }
; __global__ void __launch_bounds__(256, 2) fwd_kernel(Params p, int ph_lo, int ph_hi, int coop) {
;   __shared__ __attribute__((aligned(16))) char smc[65536 - 64];
;   const int wv = __builtin_amdgcn_readfirstlane(threadIdx.x >> 6);
;     ...
;   RUN(0, 1, phase_wprep(wv, p, smc); phase_norm(wv, p, 0))
.LBB0_123:
	s_load_dwordx4 s[56:59], s[0:1], 0xe8
	v_lshrrev_b32_e32 v2, 20, v0
	v_lshrrev_b32_e32 v0, 10, v0
	v_or_b32_e32 v0, v0, v2
	s_movk_i32 s3, 0x3ff
	s_waitcnt lgkmcnt(0)
	s_add_u32 s4, s58, 0x2500000
	s_addc_u32 s5, s59, 0
	s_add_u32 s66, s58, 0x3cc40000
	v_writelane_b32 v254, s4, 5
	s_addc_u32 s67, s59, 0
	v_and_or_b32 v0, v0, s3, v38
	v_writelane_b32 v254, s5, 6
	s_add_u32 s4, s58, 0x3ccc1004
	s_addc_u32 s5, s59, 0
	v_writelane_b32 v254, s4, 7
	s_load_dwordx16 s[36:51], s[0:1], 0x0
	s_mov_b32 s55, 0
	v_writelane_b32 v254, s5, 8
	s_add_u32 s4, s58, 0x3ccc100c
	s_addc_u32 s5, s59, 0
	v_writelane_b32 v254, s4, 9
	s_cmp_eq_u32 s2, 0
	v_mbcnt_hi_u32_b32 v1, -1, v1
	v_writelane_b32 v254, s5, 10
	s_cselect_b64 s[4:5], -1, 0
	v_writelane_b32 v254, s4, 11
	s_mov_b32 s33, 0x10200
	s_movk_i32 s80, 0x90
	v_writelane_b32 v254, s5, 12
	v_writelane_b32 v254, s72, 13
	s_cmp_lg_u32 s74, 0
	s_cselect_b64 s[4:5], -1, 0
	v_writelane_b32 v254, s73, 14
	v_writelane_b32 v254, s74, 15
	v_writelane_b32 v254, s75, 16
	v_writelane_b32 v254, s4, 17
	s_add_u32 s76, s58, 0xa600000
	s_addc_u32 s77, s59, 0
	v_writelane_b32 v254, s5, 18
	v_cmp_eq_u32_e64 s[4:5], 0, v0
	s_cmpk_lt_u32 s2, 0x74e8
	v_mov_b32_e32 v0, 0
	v_writelane_b32 v254, s4, 19
	s_mov_b32 s72, 0x800000
	s_mov_b32 s73, 0x10000
	v_writelane_b32 v254, s5, 20
	s_cselect_b64 s[4:5], -1, 0
	v_writelane_b32 v254, s4, 21
	s_lshr_b32 s3, s2, 3
	s_and_b32 s86, s2, 7
	v_writelane_b32 v254, s5, 22
	s_mov_b32 s4, s2
	v_writelane_b32 v254, s4, 23
	s_add_u32 s2, s58, 0x3ccc1000
	s_movk_i32 s91, 0x70
	v_writelane_b32 v254, s5, 24
	v_writelane_b32 v254, s2, 25
	s_addc_u32 s2, s59, 0
	v_writelane_b32 v254, s2, 26
	s_add_u32 s2, s56, 0x114c4000
	v_writelane_b32 v254, s2, 27
	s_addc_u32 s2, s57, 0
	v_writelane_b32 v254, s2, 28
	s_add_u32 s0, s56, 0x214c4000
	v_writelane_b32 v254, s0, 29
	s_addc_u32 s0, s57, 0
	v_writelane_b32 v254, s0, 30
	s_add_u32 s0, s58, 0x3cd92500
	v_writelane_b32 v254, s0, 31
	s_addc_u32 s0, s59, 0
	v_writelane_b32 v254, s0, 32
	s_add_u32 s0, s58, 0x3cd9c500
	v_writelane_b32 v254, s0, 33
	s_addc_u32 s0, s59, 0
	v_writelane_b32 v254, s0, 34
	s_add_u32 s0, s58, 0x3cda0c00
	v_writelane_b32 v254, s0, 35
	s_addc_u32 s0, s59, 0
	v_writelane_b32 v254, s0, 36
	s_add_u32 s0, s58, 0x3cd9ed00
	v_writelane_b32 v254, s0, 37
	s_addc_u32 s0, s59, 0
	v_writelane_b32 v254, s0, 38
	s_add_u32 s0, s58, 0x3cd9ee00
	v_writelane_b32 v254, s0, 39
	s_addc_u32 s0, s59, 0
	v_writelane_b32 v254, s0, 40
	s_add_u32 s0, s58, 0x3cd9ef00
	v_writelane_b32 v254, s0, 41
	s_addc_u32 s0, s59, 0
	v_writelane_b32 v254, s0, 42
	s_add_u32 s0, s58, 0x3ccc3100
	v_writelane_b32 v254, s0, 43
	s_addc_u32 s0, s59, 0
	v_writelane_b32 v254, s0, 44
	s_add_u32 s0, s58, 0x3cd2ad00
	v_writelane_b32 v254, s0, 45
	s_addc_u32 s0, s59, 0
	v_writelane_b32 v254, s0, 46
	s_add_u32 s0, s58, 0x3ccc9500
	v_writelane_b32 v254, s0, 47
	s_addc_u32 s0, s59, 0
	v_writelane_b32 v254, s0, 48
	s_add_u32 s0, s58, 0x3cd8ad00
	s_addc_u32 s1, s59, 0
	v_writelane_b32 v254, s0, 49
	s_mov_b32 s2, 0xffff0010
	s_mov_b64 s[4:5], -1
	v_writelane_b32 v254, s1, 50
	s_add_u32 s0, s58, 0x3cd8c500
	s_addc_u32 s1, s59, 0
	v_writelane_b32 v254, s0, 51
	s_mov_b32 s69, 0x20000
	s_mov_b32 s68, 0x30000
	v_writelane_b32 v254, s1, 52
	s_add_u32 s0, s58, 0x3cd8dd00
	s_addc_u32 s1, s59, 0
	v_writelane_b32 v254, s0, 53
	s_mov_b32 s18, 0x1ffffc0
	s_mov_b64 s[20:21], 0xffff
	v_writelane_b32 v254, s1, 54
	s_add_u32 s0, s58, 0x3cd8f500
	s_addc_u32 s1, s59, 0
	v_writelane_b32 v254, s0, 55
	s_movk_i32 s29, 0x500
	s_mov_b32 s52, 0xbfb8aa3b
	v_writelane_b32 v254, s1, 56
	s_add_u32 s0, s58, 0x3cd90d00
	s_addc_u32 s1, s59, 0
	v_writelane_b32 v254, s0, 57
	s_mov_b32 s53, 0x3f317217
	s_mov_b32 s95, 0x7f800000
	v_writelane_b32 v254, s1, 58
	s_add_u32 s0, s58, 0x3ccc7d00
	s_addc_u32 s1, s59, 0
	v_writelane_b32 v254, s0, 59
	s_mov_b32 s94, 0x3fb8aa3b
	s_movk_i32 s70, 0x140
	v_writelane_b32 v254, s1, 60
	s_add_u32 s0, s58, 0x3cd29500
	s_addc_u32 s1, s59, 0
	v_writelane_b32 v254, s0, 61
	s_movk_i32 s71, 0x2000
	s_movk_i32 s28, 0x3000
	v_writelane_b32 v254, s1, 62
	s_add_u32 s0, s58, 0x1d00000
	v_writelane_b32 v254, s0, 63
	s_addc_u32 s0, s59, 0
	v_writelane_b32 v255, s0, 0
	s_sub_i32 s0, 0x20b, s86
	s_and_b32 s0, s0, 0x208
	v_writelane_b32 v255, s3, 1
	s_cmp_lt_u32 s3, s0
	v_writelane_b32 v255, s0, 2
	s_cselect_b64 s[0:1], -1, 0
	v_writelane_b32 v255, s0, 3
	s_movk_i32 s78, 0x110
	s_movk_i32 s79, 0x48
	v_writelane_b32 v255, s1, 4
	s_add_u32 s0, s56, 0x33c4c000
	v_writelane_b32 v255, s0, 5
	s_addc_u32 s0, s57, 0
	v_writelane_b32 v255, s0, 6
	s_add_u32 s0, s56, 0x33a4c000
	v_writelane_b32 v255, s0, 7
	s_addc_u32 s0, s57, 0
	v_writelane_b32 v255, s0, 8
	s_add_u32 s0, s56, 0x800
	s_addc_u32 s1, s57, 0
	v_writelane_b32 v255, s0, 9
	s_movk_i32 s64, 0x50
	s_mov_b32 s65, 0x5040100
	v_writelane_b32 v255, s1, 10
	v_writelane_b32 v255, s2, 11
	s_mov_b64 s[0:1], 0
	s_mov_b64 s[62:63], 0x1000
	v_writelane_b32 v255, s3, 12
	s_mov_b32 s2, 0xffff0020
	v_writelane_b32 v255, s2, 13
	s_movk_i32 s61, 0xff00
	v_mov_b32_e32 v208, 0x3a27c5ac
	v_writelane_b32 v255, s3, 14
	s_mov_b32 s2, 0xffff0030
	v_writelane_b32 v255, s2, 15
	s_mov_b32 s81, 0x40000
	s_mov_b32 s60, 0x60000
	v_writelane_b32 v255, s3, 16
	v_add_u32_e32 v209, s54, v1
	v_mov_b32_e32 v210, 0x41b17218
	v_mov_b32_e32 v211, 0xf149f2ca
	v_mov_b32_e32 v212, 0xcf00
	v_mov_b32_e32 v213, 0x4c80
	v_mov_b32_e32 v214, 0x3a80
	v_mov_b32_e32 v215, 0x7080
	v_mov_b32_e32 v216, 0x5e80
	v_mov_b32_e32 v217, 0xe300
	v_mov_b32_e32 v218, 0xd900
	s_mov_b32 s22, s55
	v_writelane_b32 v255, s86, 17
	v_writelane_b32 v255, s55, 46
	v_writelane_b32 v255, s55, 47
	v_writelane_b32 v255, s55, 48
	v_writelane_b32 v255, s55, 49
	v_writelane_b32 v255, s55, 50
	s_getreg_b32 s101, hwreg(HW_REG_XCC_ID, 0, 4)
	s_lshl_b32 s101, s101, 2
	s_mov_b32 s100, 0
	v_readlane_b32 s2, v254, 19
	v_readlane_b32 s3, v254, 20
	s_and_saveexec_b64 vcc, s[2:3]
	s_cbranch_execz .Lxb_census_done
	s_add_u32 s2, s58, 0x3ccc1040
	s_addc_u32 s3, s59, 0
	v_mov_b32_e32 v184, 1
	v_mov_b32_e32 v185, s101
	global_atomic_add v185, v184, s[2:3]

; DI void phase_mixers(int wv, const Params& p, int layer, char* smc, int dryType) {
;     ...
;   for (;;) {
;     __syncthreads();
;     if (otid == 0) s_item = atomicAdd(cnt, 1);
;     __syncthreads();
;     int it = s_item;
;     if (it >= NITEMS) break;
.Lq_gemm_done:
	v_readlane_b32 s0, v255, 50
	s_add_u32 s0, s0, 1
	v_writelane_b32 v255, s0, 50
	s_mov_b32 s0, 0
	v_writelane_b32 v255, s0, 46
	s_branch .LBB0_199

; DI int opaque_tid(int wv) { int t = wv * 64 + (int)__builtin_amdgcn_mbcnt_hi(~0u, __builtin_amdgcn_mbcnt_lo(~0u, 0u)); asm volatile("" : "+v"(t)); return t; }
; #define RUN(PH, BIT, CALL) if (ph_lo <= (PH) && (PH) <= ph_hi) { if (ONLY & (BIT)) { CALL; } if ((PH) < ph_hi && coop) cg::this_grid().sync(); }
; DI void phase_mixers(int wv, const Params& p, int layer, char* smc, int dryType) {
;   const int otid = opaque_tid(wv);
;   __shared__ int s_item;
;   int* cnt = (int*)(p.ws + wsCNT) + layer + (dryType >= 0 ? 2 : 0);
;   const bool dry = dryType >= 0;
; __global__ void __launch_bounds__(256, 2) fwd_kernel(Params p, int ph_lo, int ph_hi, int coop) {
;     ...
;   RUN(0, 1, phase_wprep(wv, p, smc); phase_norm(wv, p, 0))
; #pragma unroll
;   for (int layer = 0; layer < 2; ++layer) {
;     const int pb = 1 + 4 * layer;
;     if (layer > 0) { RUN(pb + 0, 2, phase_norm(wv, p, layer)) }
;     RUN(pb + 1, 4, phase_inproj(wv, p, layer, smc))
;     ...
;     if (ph_lo <= pb + 2 && pb + 2 <= ph_hi) {
; #pragma unroll 1
;       for (int pass = 0; pass < 2; ++pass) {
;         phase_mixers(wv, p, layer, smc, pass == 0 ? DRYTYPE : -1);
;         if (coop) cg::this_grid().sync();
;       }
;     }
;     ...
;     RUN(pb + 2, 8, phase_mixers(wv, p, layer, smc, -1))
.LBB0_196:
	v_readlane_b32 s0, v255, 20
	s_or_b32 s4, s0, 3
	s_cmp_gt_i32 s12, s4
	s_cselect_b64 s[0:1], -1, 0
	s_cmp_gt_i32 s4, s13
	s_cselect_b64 s[2:3], -1, 0
	s_or_b64 s[0:1], s[0:1], s[2:3]
	s_and_b64 vcc, exec, s[0:1]
	s_cbranch_vccnz .LBB0_850
	v_writelane_b32 v255, s55, 46
	v_writelane_b32 v255, s55, 47
	v_writelane_b32 v255, s55, 48
	v_writelane_b32 v255, s55, 49
	v_writelane_b32 v255, s55, 50
	s_mov_b32 s23, s55
	s_lshl_b64 s[0:1], s[22:23], 2
	v_readlane_b32 s2, v254, 25
	s_add_u32 s2, s2, s0
	v_readlane_b32 s0, v254, 26
	v_writelane_b32 v255, s4, 21
	s_addc_u32 s3, s0, s1
	v_writelane_b32 v255, s2, 22
	s_lshl_b32 s0, s22, 4
	s_mul_i32 s6, s22, 0x5000
	v_writelane_b32 v255, s3, 23
	v_writelane_b32 v255, s0, 24
	s_lshl_b32 s0, s22, 5
	v_writelane_b32 v255, s0, 25
	s_lshl_b64 s[0:1], s[22:23], 5
	v_writelane_b32 v255, s0, 26
	v_readlane_b32 s7, v254, 31
	s_mul_i32 s54, s22, 0x500
	v_writelane_b32 v255, s1, 27
	s_lshl_b64 s[0:1], s[22:23], 4
	v_writelane_b32 v255, s0, 28
	s_add_u32 s8, s7, s6
	v_readlane_b32 s6, v254, 32
	v_writelane_b32 v255, s1, 29
	s_addc_u32 s9, s6, 0
	v_writelane_b32 v255, s8, 30
	s_lshl_b64 s[6:7], s[54:55], 2
	s_mul_i32 s0, s22, 48
	v_writelane_b32 v255, s9, 31
	v_readlane_b32 s8, v254, 33
	s_mov_b32 s1, s55
	s_add_u32 s8, s8, s6
	v_readlane_b32 s6, v254, 34
	s_addc_u32 s9, s6, s7
	s_lshl_b64 s[0:1], s[0:1], 2
	v_readlane_b32 s6, v254, 35
	s_mul_i32 s2, s22, 0x980
	s_mov_b32 s3, s55
	v_writelane_b32 v255, s8, 32
	s_add_u32 s6, s6, s0
	v_readlane_b32 s0, v254, 36
	v_writelane_b32 v255, s9, 33
	s_addc_u32 s7, s0, s1
	s_lshl_b64 s[0:1], s[2:3], 2
	v_readlane_b32 s2, v254, 43
	v_writelane_b32 v255, s6, 34
	s_add_u32 s2, s2, s0
	v_readlane_b32 s0, v254, 44
	v_writelane_b32 v255, s7, 35
	s_addc_u32 s3, s0, s1
	s_mul_i32 s4, s22, 0xc000
	s_mov_b32 s5, s55
	v_writelane_b32 v255, s2, 36
	s_lshl_b64 s[0:1], s[4:5], 2
	v_mov_b32_e32 v1, v209
	v_writelane_b32 v255, s3, 37
	v_readlane_b32 s2, v254, 45
	s_add_u32 s2, s2, s0
	s_nop 0
	v_writelane_b32 v255, s2, 38
	v_readlane_b32 s2, v254, 46
	s_addc_u32 s2, s2, s1
	v_cmp_eq_u32_e64 s[10:11], 0, v1
	v_writelane_b32 v255, s2, 39
	v_readlane_b32 s2, v254, 47
	s_add_u32 s0, s2, s0
	v_writelane_b32 v255, s0, 40
	v_readlane_b32 s0, v254, 48
	s_addc_u32 s0, s0, s1
	s_nop 0
	v_writelane_b32 v255, s0, 41
	v_writelane_b32 v255, s22, 42
	s_nop 1
	v_writelane_b32 v255, s23, 43
	v_writelane_b32 v255, s10, 44
	s_nop 1
	v_writelane_b32 v255, s11, 45
	s_branch .LBB0_201

; DI void phase_mixers(int wv, const Params& p, int layer, char* smc, int dryType) {
;     ...
;     int it = s_item;
;     if (it >= NITEMS) break;
;     int type, b = 0, h = 0, qb = 0, cvit = 0; bool samp = false;
;     if (it < IT_RP) { type = 0; b = it / HA; h = it % HA; }
;     else if ((it -= IT_RP) < IT_CV) { type = 3; cvit = it; }
;     else if ((it -= IT_CV) < IT_MP) { type = 1; b = it / HB; h = it % HB; }
;     else if ((it -= IT_MP) < IT_RS) { type = 0; samp = true; b = it / HA; h = it % HA; }
;     else if ((it -= IT_RS) < IT_MS) { type = 1; samp = true; b = it / HB; h = it % HB; }
;     else if ((it -= IT_MS) < IT_SS) { type = 2; samp = true; b = it / HC; h = it % HC; }
;     else { it -= IT_SS; type = 2; qb = it % (SEQ / 64); int bh = it / (SEQ / 64); b = bh / HC; h = bh % HC; }
.LBB0_205:
	s_or_b64 exec, exec, s[0:1]
	s_waitcnt lgkmcnt(0)
	s_barrier
	ds_read_b32 v1, v0 offset:65472
	s_movk_i32 s0, 0x395f
	s_waitcnt lgkmcnt(0)
	v_cmp_lt_i32_e32 vcc, s0, v1
	v_readfirstlane_b32 s3, v1
	s_mov_b64 s[0:1], -1
	s_cbranch_vccnz .LBB0_200
	s_cmpk_lt_u32 s3, 0xc0
	s_cbranch_scc1 .Lq_old
	s_sub_u32 s3, s3, 0xc0
	s_cmpk_lt_u32 s3, 0x1020
	s_cbranch_scc1 .Lq_gemm
	s_sub_u32 s3, s3, 0xf60
	v_readlane_b32 s6, v255, 50
	s_cmp_eq_u32 s6, 0
	s_cbranch_scc1 .Lq_nofl
	s_waitcnt vmcnt(0)
	s_barrier
	s_and_saveexec_b64 s[0:1], s[10:11]
	s_cbranch_execz .Lq_fl1
	v_readlane_b32 s8, v255, 22
	v_readlane_b32 s9, v255, 23
	v_mov_b32_e32 v1, s6
	s_nop 3
	global_atomic_add v0, v1, s[8:9] offset:8
.Lq_fl1:
	s_or_b64 exec, exec, s[0:1]
	v_writelane_b32 v255, s55, 50
.Lq_nofl:
	s_cmpk_lt_u32 s3, 0x840
	s_cbranch_scc1 .Lq_old
	v_readlane_b32 s6, v255, 47
	s_cmp_lg_u32 s6, 0
	s_cbranch_scc1 .Lq_old
	s_and_saveexec_b64 s[0:1], s[10:11]
	s_cbranch_execz .Lq_w2
	v_readlane_b32 s6, v255, 22
	v_readlane_b32 s7, v255, 23
	s_mov_b32 s8, 0x20000
	s_nop 2

; DI float bf2f(u16 v) { return __uint_as_float(((unsigned)v) << 16); }
; DI float silu(float x) { return x * frcp(1.f + __expf(-x)); }
; DI unsigned uidx(long row, int col) { return ((unsigned)(col >> 6) * (unsigned)MT + (unsigned)row) * 64u + (unsigned)(col & 63); }
; DI void sb_item(int wv, const Params& p, int layer, int b, int h, int qb, bool samp, char* smc, bool dry) {
;     ...
; #pragma unroll
;   for (int j = 0; j < 4; ++j) {
;     const int ql = 16 * wave + 4 * fq + j;
;     if (!dry && ql < nq) {
; #pragma unroll
;       for (int dn = 0; dn < 4; ++dn) {
;         u16* gp = U + uidx(rowq0 + ql, cGC + h * 64 + 16 * dn + fr);
;         *gp = f2bf(O[dn][j] * silu(bf2f(*gp)));
;       }
;     }
;   }
.LBB0_439:
	s_add_i32 s84, s84, 0x183000
	s_waitcnt vmcnt(0)
	s_and_saveexec_b64 s[0:1], s[12:13]
	v_add_u32_e32 v1, s84, v99
	v_lshl_or_b32 v2, v1, 6, v86
	v_mov_b32_e32 v3, v0
	v_lshl_add_u64 v[220:221], v[2:3], 1, s[76:77]
	global_load_ushort v228, v[220:221], off
	global_load_ushort v229, v[220:221], off offset:32
	global_load_ushort v230, v[220:221], off offset:64
	global_load_ushort v231, v[220:221], off offset:96
	s_or_b64 exec, exec, s[0:1]
	s_and_saveexec_b64 s[0:1], s[10:11]
	v_add_u32_e32 v1, s84, v104
	v_lshl_or_b32 v2, v1, 6, v86
	v_mov_b32_e32 v3, v0
	v_lshl_add_u64 v[222:223], v[2:3], 1, s[76:77]
	global_load_ushort v232, v[222:223], off
	global_load_ushort v233, v[222:223], off offset:32
	global_load_ushort v234, v[222:223], off offset:64
	global_load_ushort v235, v[222:223], off offset:96
	s_or_b64 exec, exec, s[0:1]
	s_and_saveexec_b64 s[0:1], s[8:9]
	v_add_u32_e32 v1, s84, v103
	v_lshl_or_b32 v2, v1, 6, v86
	v_mov_b32_e32 v3, v0
	v_lshl_add_u64 v[224:225], v[2:3], 1, s[76:77]
	global_load_ushort v236, v[224:225], off
	global_load_ushort v237, v[224:225], off offset:32
	global_load_ushort v238, v[224:225], off offset:64
	global_load_ushort v239, v[224:225], off offset:96
	s_or_b64 exec, exec, s[0:1]
	s_and_saveexec_b64 s[0:1], s[6:7]
	v_add_u32_e32 v1, s84, v102
	v_lshl_or_b32 v2, v1, 6, v86
	v_mov_b32_e32 v3, v0
	v_lshl_add_u64 v[226:227], v[2:3], 1, s[76:77]
	global_load_ushort v240, v[226:227], off
	global_load_ushort v241, v[226:227], off offset:32
	global_load_ushort v242, v[226:227], off offset:64
	global_load_ushort v243, v[226:227], off offset:96
	s_or_b64 exec, exec, s[0:1]
	s_waitcnt vmcnt(0)
	s_and_saveexec_b64 s[0:1], s[12:13]
	v_lshlrev_b32_e32 v1, 16, v228
	v_mul_f32_e32 v3, 0xbfb8aa3b, v1
	v_exp_f32_e32 v3, v3
	s_nop 0
	v_add_f32_e32 v3, 1.0, v3
	v_rcp_f32_e32 v3, v3
	s_nop 0
	v_mul_f32_e32 v1, v3, v1
	v_mul_f32_e32 v1, v46, v1
	v_cvt_pk_bf16_f32 v1, v1, s0
	global_store_short v[220:221], v1, off
	v_lshlrev_b32_e32 v1, 16, v229
	v_mul_f32_e32 v3, 0xbfb8aa3b, v1
	v_exp_f32_e32 v3, v3
	s_nop 0
	v_add_f32_e32 v3, 1.0, v3
	v_rcp_f32_e32 v3, v3
	s_nop 0
	v_mul_f32_e32 v1, v3, v1
	v_mul_f32_e32 v1, v42, v1
	v_cvt_pk_bf16_f32 v1, v1, s0
	global_store_short v[220:221], v1, off offset:32
	v_lshlrev_b32_e32 v1, 16, v230
	v_mul_f32_e32 v3, 0xbfb8aa3b, v1
	v_exp_f32_e32 v3, v3
	s_nop 0
	v_add_f32_e32 v3, 1.0, v3
	v_rcp_f32_e32 v3, v3
	s_nop 0
	v_mul_f32_e32 v1, v3, v1
	v_mul_f32_e32 v1, v38, v1
	v_cvt_pk_bf16_f32 v1, v1, s0
	global_store_short v[220:221], v1, off offset:64
	v_lshlrev_b32_e32 v1, 16, v231
	v_mul_f32_e32 v3, 0xbfb8aa3b, v1
	v_exp_f32_e32 v3, v3
	s_nop 0
	v_add_f32_e32 v3, 1.0, v3
	v_rcp_f32_e32 v3, v3
	s_nop 0
	v_mul_f32_e32 v1, v3, v1
	v_mul_f32_e32 v1, v34, v1
	v_cvt_pk_bf16_f32 v1, v1, s0
	global_store_short v[220:221], v1, off offset:96
	s_or_b64 exec, exec, s[0:1]
	s_and_saveexec_b64 s[0:1], s[10:11]
	v_lshlrev_b32_e32 v1, 16, v232
	v_mul_f32_e32 v3, 0xbfb8aa3b, v1
	v_exp_f32_e32 v3, v3
	s_nop 0
	v_add_f32_e32 v3, 1.0, v3
	v_rcp_f32_e32 v3, v3
	s_nop 0
	v_mul_f32_e32 v1, v3, v1
	v_mul_f32_e32 v1, v47, v1
	v_cvt_pk_bf16_f32 v1, v1, s0
	global_store_short v[222:223], v1, off
	v_lshlrev_b32_e32 v1, 16, v233
	v_mul_f32_e32 v3, 0xbfb8aa3b, v1
	v_exp_f32_e32 v3, v3
	s_nop 0
	v_add_f32_e32 v3, 1.0, v3
	v_rcp_f32_e32 v3, v3
	s_nop 0
	v_mul_f32_e32 v1, v3, v1
	v_mul_f32_e32 v1, v43, v1
	v_cvt_pk_bf16_f32 v1, v1, s0
	global_store_short v[222:223], v1, off offset:32
	v_lshlrev_b32_e32 v1, 16, v234
	v_mul_f32_e32 v3, 0xbfb8aa3b, v1
	v_exp_f32_e32 v3, v3
	s_nop 0
	v_add_f32_e32 v3, 1.0, v3
	v_rcp_f32_e32 v3, v3
	s_nop 0
	v_mul_f32_e32 v1, v3, v1
	v_mul_f32_e32 v1, v39, v1
	v_cvt_pk_bf16_f32 v1, v1, s0
	global_store_short v[222:223], v1, off offset:64
	v_lshlrev_b32_e32 v1, 16, v235
	v_mul_f32_e32 v3, 0xbfb8aa3b, v1
	v_exp_f32_e32 v3, v3
	s_nop 0
	v_add_f32_e32 v3, 1.0, v3
	v_rcp_f32_e32 v3, v3
	s_nop 0
	v_mul_f32_e32 v1, v3, v1
	v_mul_f32_e32 v1, v35, v1
	v_cvt_pk_bf16_f32 v1, v1, s0
	global_store_short v[222:223], v1, off offset:96
	s_or_b64 exec, exec, s[0:1]
	s_and_saveexec_b64 s[0:1], s[8:9]
	v_lshlrev_b32_e32 v1, 16, v236
	v_mul_f32_e32 v3, 0xbfb8aa3b, v1
	v_exp_f32_e32 v3, v3
	s_nop 0
	v_add_f32_e32 v3, 1.0, v3
	v_rcp_f32_e32 v3, v3
	s_nop 0
	v_mul_f32_e32 v1, v3, v1
	v_mul_f32_e32 v1, v48, v1
	v_cvt_pk_bf16_f32 v1, v1, s0
	global_store_short v[224:225], v1, off
	v_lshlrev_b32_e32 v1, 16, v237
	v_mul_f32_e32 v3, 0xbfb8aa3b, v1
	v_exp_f32_e32 v3, v3
	s_nop 0
	v_add_f32_e32 v3, 1.0, v3
	v_rcp_f32_e32 v3, v3
	s_nop 0
	v_mul_f32_e32 v1, v3, v1
	v_mul_f32_e32 v1, v44, v1
	v_cvt_pk_bf16_f32 v1, v1, s0
	global_store_short v[224:225], v1, off offset:32
	v_lshlrev_b32_e32 v1, 16, v238
	v_mul_f32_e32 v3, 0xbfb8aa3b, v1
	v_exp_f32_e32 v3, v3
	s_nop 0
	v_add_f32_e32 v3, 1.0, v3
	v_rcp_f32_e32 v3, v3
	s_nop 0
	v_mul_f32_e32 v1, v3, v1
	v_mul_f32_e32 v1, v40, v1
	v_cvt_pk_bf16_f32 v1, v1, s0
	global_store_short v[224:225], v1, off offset:64
	v_lshlrev_b32_e32 v1, 16, v239
	v_mul_f32_e32 v3, 0xbfb8aa3b, v1
	v_exp_f32_e32 v3, v3
	s_nop 0
	v_add_f32_e32 v3, 1.0, v3
	v_rcp_f32_e32 v3, v3
	s_nop 0
	v_mul_f32_e32 v1, v3, v1
	v_mul_f32_e32 v1, v36, v1
	v_cvt_pk_bf16_f32 v1, v1, s0
	global_store_short v[224:225], v1, off offset:96
	s_or_b64 exec, exec, s[0:1]
	s_and_saveexec_b64 s[0:1], s[6:7]
	v_lshlrev_b32_e32 v1, 16, v240
	v_mul_f32_e32 v3, 0xbfb8aa3b, v1
	v_exp_f32_e32 v3, v3
	s_nop 0
	v_add_f32_e32 v3, 1.0, v3
	v_rcp_f32_e32 v3, v3
	s_nop 0
	v_mul_f32_e32 v1, v3, v1
	v_mul_f32_e32 v1, v49, v1
	v_cvt_pk_bf16_f32 v1, v1, s0
	global_store_short v[226:227], v1, off
	v_lshlrev_b32_e32 v1, 16, v241
	v_mul_f32_e32 v3, 0xbfb8aa3b, v1
	v_exp_f32_e32 v3, v3
	s_nop 0
	v_add_f32_e32 v3, 1.0, v3
	v_rcp_f32_e32 v3, v3
	s_nop 0
	v_mul_f32_e32 v1, v3, v1
	v_mul_f32_e32 v1, v45, v1
	v_cvt_pk_bf16_f32 v1, v1, s0
	global_store_short v[226:227], v1, off offset:32
	v_lshlrev_b32_e32 v1, 16, v242
	v_mul_f32_e32 v3, 0xbfb8aa3b, v1
	v_exp_f32_e32 v3, v3
	s_nop 0
	v_add_f32_e32 v3, 1.0, v3
	v_rcp_f32_e32 v3, v3
	s_nop 0
	v_mul_f32_e32 v1, v3, v1
	v_mul_f32_e32 v1, v41, v1
	v_cvt_pk_bf16_f32 v1, v1, s0
	global_store_short v[226:227], v1, off offset:64
	v_lshlrev_b32_e32 v1, 16, v243
	v_mul_f32_e32 v3, 0xbfb8aa3b, v1
	v_exp_f32_e32 v3, v3
	s_nop 0
	v_add_f32_e32 v3, 1.0, v3
	v_rcp_f32_e32 v3, v3
	s_nop 0
	v_mul_f32_e32 v1, v3, v1
	v_mul_f32_e32 v1, v37, v1
	v_cvt_pk_bf16_f32 v1, v1, s0
	global_store_short v[226:227], v1, off offset:96
	s_or_b64 exec, exec, s[0:1]
	s_branch .Lsb_done
; DI void conv_item(int wv, const Params& p, int layer, int it) {
;     ...
;     const bool samp = it >= NB * 20;
;     const int ii = samp ? it - NB * 20 : it;
;     const int b = ii / 20, cb = ii % 20;
;     const int T = samp ? SSEQ : SEQ;
;     const int RL = samp ? 1 : 128;
;     const bool active = samp ? (run < 16) : true;
;     const long row0 = samp ? (long)MP + b * SSEQ : (long)b * SEQ;
;     const int chan = cb * 64 + c8 * 8;
;     const float* cw = PW(p, 21) + (size_t)layer * 4 * CD + chan;
;     const float* cbp = PW(p, 22) + layer * CD + chan;
;     const float* conv0 = p.in[5] + ((size_t)layer * NSB + b) * 3 * CD + chan;
;     float* co = p.out + (samp ? oSCV + ((size_t)layer * NSB + b) * 3 * CD : oPCV + ((size_t)layer * NB + b) * 3 * CD) + chan;
.LBB0_444:
	s_or_b64 exec, exec, s[0:1]
.Lsb_done:
	s_mov_b64 s[0:1], 0
.LBB0_445:
	s_and_b64 vcc, exec, s[0:1]
	s_cbranch_vccz .LBB0_492
	s_cmpk_gt_u32 s54, 0x13f
	s_cselect_b64 s[14:15], -1, 0
	s_add_i32 s0, s54, 0xfec0
	s_cmpk_lt_u32 s54, 0x140
	s_cselect_b64 s[10:11], -1, 0
	s_and_b64 vcc, s[10:11], exec
	s_cselect_b32 s3, s54, s0
	s_and_b32 s0, s3, 0xffff
	s_mul_i32 s0, s0, 0xcccd
	s_lshr_b32 s2, s0, 20
	v_readlane_b32 s0, v255, 26
	s_add_i32 s8, s0, s2
	s_waitcnt vmcnt(1)
	v_mov_b32_e32 v90, v209
	v_readlane_b32 s1, v255, 27
	s_mul_hi_u32 s17, s8, 0xf00
	s_mul_i32 s16, s8, 0xf00
	s_mov_b64 s[6:7], -1
	s_cbranch_vccnz .LBB0_448
	s_lshl_b32 s0, s2, 4
	s_or_b32 s4, s0, 0x10000
	s_add_u32 s0, s16, 0xce57000
	s_addc_u32 s1, s17, 0
	s_mov_b64 s[6:7], 0

; DI void phase_mixers(int wv, const Params& p, int layer, char* smc, int dryType) {
;     ...
;     int it = s_item;
;     if (it >= NITEMS) break;
.LBB0_833:
	s_or_b64 exec, exec, s[0:1]
	s_cbranch_execz .LBB0_494
	s_branch .LBB0_630
.LBB0_837:
	v_mov_b32_e32 v2, v0
	v_mov_b32_e32 v3, v0
	v_mov_b32_e32 v1, v0
	v_mov_b64_e32 v[66:67], v[2:3]
	v_mov_b64_e32 v[46:47], v[2:3]
	v_mov_b64_e32 v[70:71], v[2:3]
	v_mov_b64_e32 v[64:65], v[0:1]
	v_mov_b64_e32 v[44:45], v[0:1]
	v_mov_b64_e32 v[68:69], v[0:1]
	s_andn2_saveexec_b64 s[12:13], s[12:13]
	s_cbranch_execnz .LBB0_463
	s_branch .LBB0_464
.LBB0_838:
	v_readlane_b32 s6, v255, 50
	s_cmp_eq_u32 s6, 0
	s_cbranch_scc1 .Lq_nofl2
	s_waitcnt vmcnt(0)
	s_barrier
	v_readlane_b32 s10, v255, 44
	v_readlane_b32 s11, v255, 45
	s_and_saveexec_b64 s[0:1], s[10:11]
	s_cbranch_execz .Lq_fl2
	v_readlane_b32 s8, v255, 22
	v_readlane_b32 s9, v255, 23
	v_mov_b32_e32 v1, s6
	s_nop 3
	global_atomic_add v0, v1, s[8:9] offset:8
